# GEMM epilogue head: the eight pointer-table LDS reads issued together with one wait instead of eight serial round trips
# speedup vs baseline: 1.0006x; 1.0006x over previous
.LBB0_90:
	v_mov_b32_e32 v194, s88
	v_mov_b32_e32 v195, s89
	v_readlane_b32 s2, v254, 44
	v_readlane_b32 s3, v254, 45
	ds_read_b32 v194, v194
	ds_read_b32 v195, v195
	v_mov_b32_e32 v196, s2
	v_mov_b32_e32 v197, s3
	v_readlane_b32 s2, v254, 31
	v_readlane_b32 s3, v254, 46
	ds_read_b32 v196, v196
	ds_read_b32 v197, v197
	v_mov_b32_e32 v198, s2
	v_mov_b32_e32 v199, s3
	v_readlane_b32 s2, v254, 39
	v_readlane_b32 s3, v254, 48
	ds_read_b32 v198, v198
	ds_read_b32 v199, v199
	v_mov_b32_e32 v200, s2
	v_mov_b32_e32 v201, s3
	ds_read_b32 v200, v200
	ds_read_b32 v201, v201
	v_mov_b32_e32 v151, v153
	s_mov_b64 s[58:59], -1
	s_mov_b64 s[56:57], 0
	s_lshl_b32 s62, s10, 8
	s_lshl_b32 s27, s67, 8
	v_readlane_b32 s2, v254, 40
	s_add_i32 s62, s62, s2
	s_ashr_i32 s2, s62, 13
	s_mul_i32 s54, s2, 0x1800
	s_ashr_i32 s55, s54, 31
	v_or_b32_e32 v138, s62, v157
	v_ashrrev_i32_e32 v139, 31, v138
	s_waitcnt lgkmcnt(0)
	v_readfirstlane_b32 s48, v194
	v_readfirstlane_b32 s49, v195
	v_readfirstlane_b32 s42, v196
	v_readfirstlane_b32 s43, v197
	v_readfirstlane_b32 s65, v198
	v_readfirstlane_b32 s66, v199
	v_readfirstlane_b32 s44, v200
	v_readfirstlane_b32 s45, v201
	s_add_u32 s52, s48, 0x2100000
	s_addc_u32 s53, s49, 0
	s_add_u32 s46, s48, 0x158d0000
	s_addc_u32 s47, s49, 0
	s_add_u32 s40, s48, 0xc600000
	s_addc_u32 s41, s49, 0
	s_add_u32 s36, s48, 0xe700000
	s_addc_u32 s37, s49, 0
	s_add_u32 s34, s48, 0x6300000
	s_addc_u32 s35, s49, 0
	s_add_u32 s38, s48, 0x4200000
	s_addc_u32 s39, s49, 0
	s_add_u32 s50, s48, 0x15af4000
	s_addc_u32 s51, s49, 0
	v_readlane_b32 s2, v254, 26
	s_mul_i32 s2, s2, 0x12000
	s_add_u32 s2, s48, s2
	s_addc_u32 s3, s49, 0
	s_add_u32 s30, s2, 0x15ad0000
	s_addc_u32 s31, s3, 0
	v_lshlrev_b64 v[136:137], 13, v[138:139]
	v_add_u32_e32 v150, 0xffffc000, v138
	v_lshl_add_u64 v[148:149], s[52:53], 0, v[136:137]
	v_cmp_gt_i32_e64 s[10:11], s92, v138
	v_cmp_lt_i32_e64 s[8:9], s80, v138
	v_lshlrev_b64 v[146:147], 10, v[150:151]
	v_lshlrev_b64 v[142:143], 10, v[138:139]
	v_or_b32_e32 v136, s27, v161
	s_cmp_lt_i32 s79, 22
	s_mov_b64 s[2:3], 0
	s_cbranch_scc1 .LBB0_117
	s_cmp_gt_i32 s79, 23
	s_cbranch_scc0 .LBB0_111
	s_cmp_gt_i32 s79, 24
	s_cbranch_scc0 .LBB0_108
	s_cmp_gt_i32 s79, 25
	s_cbranch_scc0 .LBB0_97
	s_cmp_eq_u32 s79, 26
	s_mov_b64 s[2:3], -1
	s_cbranch_scc0 .LBB0_96
	v_max_f32_e32 v137, v124, v124
	v_max_f32_e32 v137, 0, v137
	v_max_f32_e32 v140, v120, v120
	v_max_f32_e32 v140, 0, v140
	v_mul_f32_e32 v144, v137, v137
	v_max_f32_e32 v137, v125, v125
	v_mul_f32_e32 v152, v140, v140
	v_max_f32_e32 v137, 0, v137
	v_max_f32_e32 v140, v121, v121
	v_max_f32_e32 v140, 0, v140
	v_mul_f32_e32 v145, v137, v137
	v_max_f32_e32 v137, v126, v126
	v_mul_f32_e32 v166, v140, v140
	v_max_f32_e32 v137, 0, v137
	v_max_f32_e32 v140, v122, v122
	v_max_f32_e32 v140, 0, v140
	v_mul_f32_e32 v167, v137, v137
	v_max_f32_e32 v137, v127, v127
	v_mul_f32_e32 v168, v140, v140
	v_max_f32_e32 v137, 0, v137
	v_max_f32_e32 v140, v123, v123
	v_max_f32_e32 v140, 0, v140
	v_mul_f32_e32 v169, v137, v137
	v_ashrrev_i32_e32 v137, 31, v136
	v_mul_f32_e32 v170, v140, v140
	v_lshl_add_u64 v[140:141], v[136:137], 1, v[148:149]
	v_cvt_pk_bf16_f32 v144, v144, v145
	v_cvt_pk_bf16_f32 v145, v167, v169
	global_store_dwordx2 v[140:141], v[144:145], off
	v_cvt_pk_bf16_f32 v144, v152, v166
	v_cvt_pk_bf16_f32 v145, v168, v170
	global_store_dwordx2 v[140:141], v[144:145], off offset:32
	s_mov_b64 s[2:3], 0
